# phase G sample rows: last-arriving block normalisation issues all row and weight quad loads up front, stores without per-step round trips
# speedup vs baseline: 1.0202x; 1.0058x over previous
; __device__ __forceinline__ float shfl_xor_f(float v, int mask) { const int l = lane_fresh(); return __int_as_float(__builtin_amdgcn_ds_bpermute((l ^ mask) << 2, __float_as_int(v))); }
; __device__ __forceinline__ void phaseG(const Params& p, const int wv, const int rep, unsigned* bar, const bool fused) {
;     ...
;       if (last_l[0]) {
;         __builtin_amdgcn_fence(__ATOMIC_ACQUIRE, "agent");
;         const int r = tid >> 5, c32 = tid & 31;
;         float* yrow = p.out + O_Y + (size_t)(TP + mt * 16 + r) * 1024;
;         float sq = __hip_atomic_load(XSS + (size_t)(mt * 16 + r) * 64 + c32 * 2, __ATOMIC_RELAXED, __HIP_MEMORY_SCOPE_AGENT)
;                  + __hip_atomic_load(XSS + (size_t)(mt * 16 + r) * 64 + c32 * 2 + 1, __ATOMIC_RELAXED, __HIP_MEMORY_SCOPE_AGENT);
;         sq += shfl_xor_f(sq, 16); sq += shfl_xor_f(sq, 8); sq += shfl_xor_f(sq, 4); sq += shfl_xor_f(sq, 2); sq += shfl_xor_f(sq, 1);
;         const float rs = rsqrtf(sq * (1.f / 1024.f) + EPS);
; #pragma unroll
;         for (int i = 0; i < 8; ++i) {
;           const int col = i * 128 + c32 * 4;
;           f32x4 v = *(const f32x4*)(yrow + col);
;           *(f32x4*)(yrow + col) = v * rs * *(const f32x4*)(wfin + col);
;         }
;       }
.LBB0_1200:
	s_or_b64 exec, exec, s[24:25]
	s_waitcnt lgkmcnt(0)
	s_barrier
	ds_read_b32 v2, v15 offset:32768
	s_waitcnt lgkmcnt(0)
	v_cmp_eq_u32_e32 vcc, 0, v2
	s_cbranch_vccnz .LBB0_1182
	v_ashrrev_i32_e32 v2, 5, v1
	v_and_b32_e32 v3, 31, v0
	v_add_u32_e32 v0, s22, v2
	v_ashrrev_i32_e32 v1, 31, v0
	v_lshlrev_b64 v[0:1], 8, v[0:1]
	v_lshl_add_u64 v[0:1], s[10:11], 0, v[0:1]
	v_lshlrev_b32_e32 v4, 3, v3
	v_lshl_add_u64 v[0:1], v[0:1], 0, v[4:5]
	s_waitcnt vmcnt(0)
	buffer_inv sc1
	global_load_dword v10, v[0:1], off sc1
	global_load_dword v11, v[0:1], off offset:4 sc1
	v_add_u32_e32 v0, s20, v2
	v_ashrrev_i32_e32 v1, 31, v0
	v_lshlrev_b64 v[0:1], 12, v[0:1]
	v_lshl_add_u64 v[0:1], s[48:49], 0, v[0:1]
	v_lshlrev_b32_e32 v4, 4, v3
	v_lshl_add_u64 v[16:17], v[0:1], 0, v[4:5]
	v_mbcnt_lo_u32_b32 v12, -1, 0
	v_mbcnt_hi_u32_b32 v12, -1, v12
	v_mbcnt_lo_u32_b32 v13, -1, 0
	v_mbcnt_hi_u32_b32 v13, -1, v13
	v_mbcnt_lo_u32_b32 v18, -1, 0
	v_mbcnt_hi_u32_b32 v18, -1, v18
	v_mbcnt_lo_u32_b32 v19, -1, 0
	v_mbcnt_hi_u32_b32 v19, -1, v19
	v_mbcnt_lo_u32_b32 v20, -1, 0
	v_mbcnt_hi_u32_b32 v20, -1, v20
	global_load_dwordx4 v[60:63], v[16:17], off
	global_load_dwordx4 v[92:95], v4, s[46:47]
	global_load_dwordx4 v[64:67], v[16:17], off offset:512
	global_load_dwordx4 v[96:99], v4, s[46:47] offset:512
	global_load_dwordx4 v[68:71], v[16:17], off offset:1024
	global_load_dwordx4 v[100:103], v4, s[46:47] offset:1024
	global_load_dwordx4 v[72:75], v[16:17], off offset:1536
	global_load_dwordx4 v[104:107], v4, s[46:47] offset:1536
	global_load_dwordx4 v[76:79], v[16:17], off offset:2048
	global_load_dwordx4 v[108:111], v4, s[46:47] offset:2048
	global_load_dwordx4 v[80:83], v[16:17], off offset:2560
	global_load_dwordx4 v[112:115], v4, s[46:47] offset:2560
	global_load_dwordx4 v[84:87], v[16:17], off offset:3072
	global_load_dwordx4 v[116:119], v4, s[46:47] offset:3072
	global_load_dwordx4 v[88:91], v[16:17], off offset:3584
	global_load_dwordx4 v[120:123], v4, s[46:47] offset:3584
	v_lshlrev_b32_e32 v12, 2, v12
	v_xor_b32_e32 v12, 64, v12
	s_waitcnt vmcnt(16)
	v_add_f32_e32 v10, v11, v10
	ds_bpermute_b32 v11, v12, v10
	v_lshlrev_b32_e32 v12, 2, v13
	v_xor_b32_e32 v12, 32, v12
	s_waitcnt lgkmcnt(0)
	v_add_f32_e32 v10, v10, v11
	ds_bpermute_b32 v11, v12, v10
	v_lshlrev_b32_e32 v12, 2, v18
	v_xor_b32_e32 v12, 16, v12
	s_waitcnt lgkmcnt(0)
	v_add_f32_e32 v10, v10, v11
	ds_bpermute_b32 v11, v12, v10
	v_lshlrev_b32_e32 v12, 2, v19
	v_xor_b32_e32 v12, 8, v12
	s_waitcnt lgkmcnt(0)
	v_add_f32_e32 v10, v10, v11
	ds_bpermute_b32 v11, v12, v10
	v_lshlrev_b32_e32 v12, 2, v20
	v_xor_b32_e32 v12, 4, v12
	s_waitcnt lgkmcnt(0)
	v_add_f32_e32 v10, v10, v11
	ds_bpermute_b32 v11, v12, v10
	s_waitcnt lgkmcnt(0)
	v_add_f32_e32 v10, v10, v11
	v_fmamk_f32 v10, v10, 0x3a800000, v14
	v_mul_f32_e32 v11, 0x4b800000, v10
	v_cmp_gt_f32_e32 vcc, s37, v10
	s_nop 1
	v_cndmask_b32_e32 v10, v10, v11, vcc
	v_rsq_f32_e32 v18, v10
	v_mul_f32_e32 v19, 0x45800000, v18
	v_cndmask_b32_e32 v18, v18, v19, vcc
	s_waitcnt vmcnt(14)
	v_pk_mul_f32 v[60:61], v[60:61], v[18:19] op_sel_hi:[1,0]
	v_pk_mul_f32 v[62:63], v[62:63], v[18:19] op_sel_hi:[1,0]
	v_pk_mul_f32 v[60:61], v[92:93], v[60:61]
	v_pk_mul_f32 v[62:63], v[94:95], v[62:63]
	global_store_dwordx4 v[16:17], v[60:63], off sc1
	s_waitcnt vmcnt(13)
	v_pk_mul_f32 v[64:65], v[64:65], v[18:19] op_sel_hi:[1,0]
	v_pk_mul_f32 v[66:67], v[66:67], v[18:19] op_sel_hi:[1,0]
	v_pk_mul_f32 v[64:65], v[96:97], v[64:65]
	v_pk_mul_f32 v[66:67], v[98:99], v[66:67]
	global_store_dwordx4 v[16:17], v[64:67], off offset:512 sc1
	s_waitcnt vmcnt(12)
	v_pk_mul_f32 v[68:69], v[68:69], v[18:19] op_sel_hi:[1,0]
	v_pk_mul_f32 v[70:71], v[70:71], v[18:19] op_sel_hi:[1,0]
	v_pk_mul_f32 v[68:69], v[100:101], v[68:69]
	v_pk_mul_f32 v[70:71], v[102:103], v[70:71]
	global_store_dwordx4 v[16:17], v[68:71], off offset:1024 sc1
	s_waitcnt vmcnt(11)
	v_pk_mul_f32 v[72:73], v[72:73], v[18:19] op_sel_hi:[1,0]
	v_pk_mul_f32 v[74:75], v[74:75], v[18:19] op_sel_hi:[1,0]
	v_pk_mul_f32 v[72:73], v[104:105], v[72:73]
	v_pk_mul_f32 v[74:75], v[106:107], v[74:75]
	global_store_dwordx4 v[16:17], v[72:75], off offset:1536 sc1
	s_waitcnt vmcnt(10)
	v_pk_mul_f32 v[76:77], v[76:77], v[18:19] op_sel_hi:[1,0]
	v_pk_mul_f32 v[78:79], v[78:79], v[18:19] op_sel_hi:[1,0]
	v_pk_mul_f32 v[76:77], v[108:109], v[76:77]
	v_pk_mul_f32 v[78:79], v[110:111], v[78:79]
	global_store_dwordx4 v[16:17], v[76:79], off offset:2048 sc1
	s_waitcnt vmcnt(9)
	v_pk_mul_f32 v[80:81], v[80:81], v[18:19] op_sel_hi:[1,0]
	v_pk_mul_f32 v[82:83], v[82:83], v[18:19] op_sel_hi:[1,0]
	v_pk_mul_f32 v[80:81], v[112:113], v[80:81]
	v_pk_mul_f32 v[82:83], v[114:115], v[82:83]
	global_store_dwordx4 v[16:17], v[80:83], off offset:2560 sc1
	s_waitcnt vmcnt(8)
	v_pk_mul_f32 v[84:85], v[84:85], v[18:19] op_sel_hi:[1,0]
	v_pk_mul_f32 v[86:87], v[86:87], v[18:19] op_sel_hi:[1,0]
	v_pk_mul_f32 v[84:85], v[116:117], v[84:85]
	v_pk_mul_f32 v[86:87], v[118:119], v[86:87]
	global_store_dwordx4 v[16:17], v[84:87], off offset:3072 sc1
	s_waitcnt vmcnt(7)
	v_pk_mul_f32 v[88:89], v[88:89], v[18:19] op_sel_hi:[1,0]
	v_pk_mul_f32 v[90:91], v[90:91], v[18:19] op_sel_hi:[1,0]
	v_pk_mul_f32 v[88:89], v[120:121], v[88:89]
	v_pk_mul_f32 v[90:91], v[122:123], v[90:91]
	global_store_dwordx4 v[16:17], v[88:91], off offset:3584 sc1
	s_branch .LBB0_1182
